# moba_select prologue: block-mean load issued ahead of the rendezvous barrier (was after it)
# speedup vs baseline: 1.0028x; 1.0028x over previous
; #define LAS __attribute__((address_space(3)))
; __device__ __forceinline__ void moba_select(LAS unsigned char* lds, const bf16_t* Qp, int ld, int rowbase, int ob, const float* kmean_bh) {
;     ...
;     __syncthreads();
;     ((LAS f32x4*)km_s)[tid] = ((const f32x4*)kmean_bh)[tid];
;     __syncthreads();
;     { const int q = tid >> 1, par = tid & 1; const bf16_t* qrow = Qp + (size_t)(rowbase + ob * 256 + q) * ld;
.LBB0_889:
	global_load_dwordx4 v[24:27], v[154:155], off
	s_barrier
	s_xor_b64 s[52:53], s[54:55], -1
	s_and_b64 s[2:3], s[54:55], exec
	s_cselect_b32 s35, s65, s64
	s_lshl_b32 s36, s35, 8
	s_waitcnt vmcnt(22)
	v_mov_b64_e32 v[28:29], s[50:51]
	v_mov_b32_e32 v6, v1
	v_mov_b32_e32 v7, v1
	v_add_u32_e32 v30, s36, v149
	v_mov_b32_e32 v0, v1
	v_mov_b32_e32 v2, v1
	v_mov_b32_e32 v3, v1
	v_mov_b32_e32 v4, v1
	v_mov_b32_e32 v5, v1
	v_mad_i64_i32 v[32:33], s[16:17], v30, s94, v[28:29]
	s_mov_b32 s18, 0
	v_cmp_gt_u32_e32 vcc, s35, v172
	v_cmp_gt_u32_e64 s[2:3], s35, v173
	v_cmp_gt_u32_e64 s[4:5], s35, v174
	v_cmp_gt_u32_e64 s[6:7], s35, v175
	v_cmp_gt_u32_e64 s[8:9], s35, v176
	v_cmp_gt_u32_e64 s[10:11], s35, v177
	v_cmp_gt_u32_e64 s[12:13], s35, v178
	v_cmp_gt_u32_e64 s[14:15], s35, v179
	s_waitcnt vmcnt(0)
	ds_write_b128 v170, v[24:27]
	v_mov_b64_e32 v[30:31], v[6:7]
	v_mov_b64_e32 v[28:29], v[4:5]
	v_mov_b64_e32 v[26:27], v[2:3]
	v_mov_b64_e32 v[24:25], v[0:1]
	global_load_dwordx4 v[230:233], v[32:33], off
	s_waitcnt lgkmcnt(0)
	s_barrier
	s_branch .LBB0_891
